# att9 = att7 + cross-half row-max merge (mov, nop, permlane32_swap, max) moved out of the per-step decision chain into the rare rescale path
# baseline (speedup 1.0000x reference)
.LBB0_300:
	s_lshl_b32 s0, s0, 1
	v_add_u32_e32 v0, s0, v248
	ds_read_b64_tr_b16 v[2:3], v0 offset:24576
	ds_read_b64_tr_b16 v[4:5], v0 offset:25088
	s_waitcnt lgkmcnt(9)
	v_mfma_f32_32x32x16_bf16 v[144:159], v[220:223], v[188:191], v[80:95]
	v_add_f32_e32 v6, v112, v113
	v_add_f32_e32 v6, v114, v6
	v_add_f32_e32 v6, v115, v6
	v_add_f32_e32 v6, v116, v6
	v_add_f32_e32 v10, v117, v6
	v_cvt_pk_bf16_f32 v180, v112, v113
	v_cvt_pk_bf16_f32 v181, v114, v115
	ds_read_b64_tr_b16 v[6:7], v0 offset:28672
	ds_read_b64_tr_b16 v[8:9], v0 offset:29184
	s_waitcnt lgkmcnt(10)
	v_mfma_f32_32x32x16_bf16 v[128:143], v[216:219], v[188:191], v[80:95]
	v_add_f32_e32 v10, v118, v10
	v_add_f32_e32 v10, v119, v10
	v_add_f32_e32 v10, v120, v10
	v_add_f32_e32 v14, v121, v10
	v_cvt_pk_bf16_f32 v182, v116, v117
	v_cvt_pk_bf16_f32 v183, v118, v119
	ds_read_b64_tr_b16 v[10:11], v0 offset:25600
	ds_read_b64_tr_b16 v[12:13], v0 offset:26112
	s_waitcnt lgkmcnt(11)
	v_mfma_f32_32x32x16_bf16 v[144:159], v[212:215], v[184:187], v[144:159]
	v_add_f32_e32 v14, v122, v14
	v_add_f32_e32 v14, v123, v14
	v_add_f32_e32 v14, v124, v14
	v_add_f32_e32 v14, v125, v14
	v_cvt_pk_bf16_f32 v172, v120, v121
	v_cvt_pk_bf16_f32 v173, v122, v123
	ds_read_b64_tr_b16 v[112:113], v0 offset:29696
	ds_read_b64_tr_b16 v[114:115], v0 offset:30208
	s_waitcnt lgkmcnt(12)
	v_mfma_f32_32x32x16_bf16 v[128:143], v[208:211], v[184:187], v[128:143]
	v_add_f32_e32 v14, v126, v14
	v_add_f32_e32 v14, v127, v14
	v_add_f32_e32 v14, v96, v14
	v_add_f32_e32 v14, v97, v14
	v_cvt_pk_bf16_f32 v174, v124, v125
	v_cvt_pk_bf16_f32 v175, v126, v127
	ds_read_b64_tr_b16 v[116:117], v0 offset:26624
	ds_read_b64_tr_b16 v[118:119], v0 offset:27136
	s_waitcnt lgkmcnt(13)
	v_mfma_f32_32x32x16_bf16 v[144:159], v[204:207], v[176:179], v[144:159]
	v_add_f32_e32 v14, v98, v14
	v_add_f32_e32 v14, v99, v14
	v_add_f32_e32 v14, v100, v14
	v_add_f32_e32 v14, v101, v14
	v_cvt_pk_bf16_f32 v164, v96, v97
	v_cvt_pk_bf16_f32 v165, v98, v99
	ds_read_b64_tr_b16 v[96:97], v0 offset:30720
	ds_read_b64_tr_b16 v[98:99], v0 offset:31232
	s_waitcnt lgkmcnt(14)
	v_mfma_f32_32x32x16_bf16 v[128:143], v[200:203], v[176:179], v[128:143]
	v_add_f32_e32 v14, v102, v14
	v_add_f32_e32 v14, v103, v14
	v_add_f32_e32 v14, v104, v14
	v_add_f32_e32 v14, v105, v14
	v_cvt_pk_bf16_f32 v166, v100, v101
	v_cvt_pk_bf16_f32 v167, v102, v103
	ds_read_b64_tr_b16 v[100:101], v0 offset:27648
	ds_read_b64_tr_b16 v[102:103], v0 offset:28160
	s_waitcnt lgkmcnt(14)
	v_mfma_f32_32x32x16_bf16 v[144:159], v[196:199], v[168:171], v[144:159]
	v_add_f32_e32 v14, v106, v14
	v_add_f32_e32 v14, v107, v14
	v_add_f32_e32 v14, v108, v14
	v_add_f32_e32 v14, v109, v14
	v_cvt_pk_bf16_f32 v160, v104, v105
	v_cvt_pk_bf16_f32 v161, v106, v107
	ds_read_b64_tr_b16 v[104:105], v0 offset:31744
	ds_read_b64_tr_b16 v[106:107], v0 offset:32256
	v_mfma_f32_32x32x16_bf16 v[128:143], v[192:195], v[168:171], v[128:143]
	v_add_f32_e32 v14, v110, v14
	v_add_f32_e32 v14, v111, v14
	v_add_f32_e32 v214, v250, v14
	v_cvt_pk_bf16_f32 v162, v108, v109
	v_cvt_pk_bf16_f32 v163, v110, v111
	s_add_i32 s0, s38, s46
	s_mov_b32 s1, m0
	s_mov_b32 m0, s0
	s_nop 0
	global_load_lds_dwordx4 v253, s[98:99]
	s_mov_b32 m0, s1
	s_waitcnt lgkmcnt(14)
	v_mfma_f32_32x32x16_bf16 v[16:31], v[180:183], v[2:5], v[16:31]
	v_max_f32_e32 v108, v144, v145
	v_max3_f32 v109, v146, v147, v129
	v_max3_f32 v108, v108, v128, v130
	v_max3_f32 v108, v108, v131, v148
	v_max3_f32 v109, v109, v150, v151
	v_max3_f32 v108, v108, v149, v132
	s_waitcnt lgkmcnt(12)
	v_mfma_f32_32x32x16_bf16 v[32:47], v[180:183], v[6:9], v[32:47]
	v_max3_f32 v109, v109, v134, v135
	v_max3_f32 v108, v108, v133, v152
	v_max3_f32 v109, v109, v154, v155
	v_max3_f32 v108, v108, v153, v136
	v_max3_f32 v109, v109, v138, v139
	v_max3_f32 v108, v108, v137, v156
	s_waitcnt lgkmcnt(10)
	v_mfma_f32_32x32x16_bf16 v[16:31], v[172:175], v[10:13], v[16:31]
	v_max3_f32 v109, v109, v158, v159
	v_max3_f32 v108, v108, v157, v140
	v_max3_f32 v109, v109, v142, v143
	v_max3_f32 v108, v108, v141, v109
	v_cmp_lt_f32_e32 vcc, s25, v108
	s_cmp_lg_u64 vcc, 0
	s_cselect_b64 s[78:79], -1, 0
	s_cbranch_vccnz .LBB0_308

.LBB0_303:
	s_add_i32 s0, s19, 0x2000
	s_cmpk_lg_i32 s19, 0x4000
	s_cselect_b32 s50, s0, 0
	s_lshl_b32 s0, s38, 1
	v_add_u32_e32 v215, s0, v248
	ds_read_b64_tr_b16 v[192:193], v215 offset:24576
	ds_read_b64_tr_b16 v[194:195], v215 offset:25088
	s_waitcnt lgkmcnt(9)
	v_mfma_f32_32x32x16_bf16 v[112:127], v[96:99], v[188:191], v[80:95]
	v_add_f32_e32 v100, v144, v145
	v_add_f32_e32 v100, v146, v100
	v_add_f32_e32 v100, v147, v100
	v_add_f32_e32 v100, v148, v100
	v_add_f32_e32 v100, v149, v100
	v_cvt_pk_bf16_f32 v180, v144, v145
	v_cvt_pk_bf16_f32 v181, v146, v147
	ds_read_b64_tr_b16 v[144:145], v215 offset:28672
	ds_read_b64_tr_b16 v[146:147], v215 offset:29184
	v_add_f32_e32 v96, v150, v100
	v_add_f32_e32 v96, v151, v96
	v_add_f32_e32 v96, v152, v96
	v_add_f32_e32 v160, v153, v96
	s_waitcnt lgkmcnt(10)
	v_mfma_f32_32x32x16_bf16 v[96:111], v[204:207], v[188:191], v[80:95]
	v_cvt_pk_bf16_f32 v182, v148, v149
	v_cvt_pk_bf16_f32 v183, v150, v151
	ds_read_b64_tr_b16 v[148:149], v215 offset:25600
	ds_read_b64_tr_b16 v[150:151], v215 offset:26112
	s_waitcnt lgkmcnt(11)
	v_mfma_f32_32x32x16_bf16 v[112:127], v[208:211], v[184:187], v[112:127]
	v_add_f32_e32 v160, v154, v160
	v_add_f32_e32 v160, v155, v160
	v_add_f32_e32 v160, v156, v160
	v_add_f32_e32 v160, v157, v160
	v_cvt_pk_bf16_f32 v172, v152, v153
	v_cvt_pk_bf16_f32 v173, v154, v155
	ds_read_b64_tr_b16 v[152:153], v215 offset:29696
	ds_read_b64_tr_b16 v[154:155], v215 offset:30208
	s_waitcnt lgkmcnt(12)
	v_mfma_f32_32x32x16_bf16 v[96:111], v[200:203], v[184:187], v[96:111]
	v_add_f32_e32 v160, v158, v160
	v_add_f32_e32 v160, v159, v160
	v_add_f32_e32 v160, v128, v160
	v_add_f32_e32 v160, v129, v160
	v_cvt_pk_bf16_f32 v174, v156, v157
	v_cvt_pk_bf16_f32 v175, v158, v159
	ds_read_b64_tr_b16 v[156:157], v215 offset:26624
	ds_read_b64_tr_b16 v[158:159], v215 offset:27136
	s_waitcnt lgkmcnt(13)
	v_mfma_f32_32x32x16_bf16 v[112:127], v[196:199], v[176:179], v[112:127]
	v_add_f32_e32 v160, v130, v160
	v_add_f32_e32 v160, v131, v160
	v_add_f32_e32 v160, v132, v160
	v_add_f32_e32 v160, v133, v160
	v_cvt_pk_bf16_f32 v164, v128, v129
	v_cvt_pk_bf16_f32 v165, v130, v131
	ds_read_b64_tr_b16 v[128:129], v215 offset:30720
	ds_read_b64_tr_b16 v[130:131], v215 offset:31232
	s_waitcnt lgkmcnt(14)
	v_mfma_f32_32x32x16_bf16 v[96:111], v[10:13], v[176:179], v[96:111]
	v_add_f32_e32 v10, v134, v160
	v_add_f32_e32 v10, v135, v10
	v_add_f32_e32 v10, v136, v10
	v_add_f32_e32 v160, v137, v10
	v_cvt_pk_bf16_f32 v166, v132, v133
	v_cvt_pk_bf16_f32 v167, v134, v135
	ds_read_b64_tr_b16 v[10:11], v215 offset:27648
	ds_read_b64_tr_b16 v[12:13], v215 offset:28160
	s_waitcnt lgkmcnt(14)
	v_mfma_f32_32x32x16_bf16 v[112:127], v[6:9], v[168:171], v[112:127]
	v_add_f32_e32 v6, v138, v160
	v_add_f32_e32 v6, v139, v6
	v_add_f32_e32 v6, v140, v6
	v_add_f32_e32 v132, v141, v6
	v_cvt_pk_bf16_f32 v160, v136, v137
	v_cvt_pk_bf16_f32 v161, v138, v139
	ds_read_b64_tr_b16 v[6:7], v215 offset:31744
	ds_read_b64_tr_b16 v[8:9], v215 offset:32256
	v_mfma_f32_32x32x16_bf16 v[96:111], v[2:5], v[168:171], v[96:111]
	v_add_f32_e32 v2, v142, v132
	v_add_f32_e32 v2, v143, v2
	v_add_f32_e32 v250, v214, v2
	v_cvt_pk_bf16_f32 v162, v140, v141
	v_cvt_pk_bf16_f32 v163, v142, v143
	s_add_i32 s0, s19, s46
	s_mov_b32 s1, m0
	s_mov_b32 m0, s0
	s_nop 0
	global_load_lds_dwordx4 v253, s[98:99]
	s_mov_b32 m0, s1
	s_waitcnt lgkmcnt(14)
	v_mfma_f32_32x32x16_bf16 v[16:31], v[180:183], v[192:195], v[16:31]
	v_max_f32_e32 v2, v112, v113
	v_max3_f32 v3, v114, v115, v97
	v_max3_f32 v2, v2, v96, v98
	v_max3_f32 v2, v2, v99, v116
	v_max3_f32 v3, v3, v118, v119
	v_max3_f32 v2, v2, v117, v100
	s_waitcnt lgkmcnt(12)
	v_mfma_f32_32x32x16_bf16 v[32:47], v[180:183], v[144:147], v[32:47]
	v_max3_f32 v3, v3, v102, v103
	v_max3_f32 v2, v2, v101, v120
	v_max3_f32 v3, v3, v122, v123
	v_max3_f32 v2, v2, v121, v104
	v_max3_f32 v3, v3, v106, v107
	v_max3_f32 v2, v2, v105, v124
	s_waitcnt lgkmcnt(10)
	v_mfma_f32_32x32x16_bf16 v[16:31], v[172:175], v[148:151], v[16:31]
	v_max3_f32 v3, v3, v126, v127
	v_max3_f32 v2, v2, v125, v108
	v_max3_f32 v3, v3, v110, v111
	v_max3_f32 v2, v2, v109, v3
	v_cmp_lt_f32_e32 vcc, s25, v2
	s_cmp_lg_u64 vcc, 0
	s_cselect_b64 s[78:79], -1, 0
	s_cbranch_vccnz .LBB0_311

.LBB0_308:
	v_mov_b32_e32 v109, v108
	s_nop 1
	v_permlane32_swap_b32_e32 v108, v109
	v_max_f32_e32 v108, v108, v109
	v_max_f32_e32 v80, v108, v108
	v_max_f32_e32 v108, 0, v80
	v_exp_f32_e64 v109, -v108
	v_add_f32_e32 v243, v243, v108
	v_xor_b32_e32 v80, 0x80000000, v243
	v_mov_b32_e32 v81, v80
	v_mov_b32_e32 v82, v80
	v_mov_b32_e32 v83, v80
	v_mov_b32_e32 v84, v80
	v_mov_b32_e32 v85, v80
	v_mov_b32_e32 v86, v80
	v_mov_b32_e32 v87, v80
	v_mov_b32_e32 v88, v80
	v_mov_b32_e32 v89, v80
	v_mov_b32_e32 v90, v80
	v_mov_b32_e32 v91, v80
	v_mov_b32_e32 v92, v80
	v_mov_b32_e32 v93, v80
	v_mov_b32_e32 v94, v80
	v_mov_b32_e32 v95, v80
	s_and_saveexec_b64 s[0:1], s[2:3]
	ds_write_b32 v240, v109
	s_or_b64 exec, exec, s[0:1]
	v_sub_f32_e32 v159, v159, v108
	v_sub_f32_e32 v158, v158, v108
	v_sub_f32_e32 v157, v157, v108
	v_sub_f32_e32 v156, v156, v108
	v_sub_f32_e32 v155, v155, v108
	v_sub_f32_e32 v154, v154, v108
	v_sub_f32_e32 v153, v153, v108
	v_sub_f32_e32 v152, v152, v108
	v_sub_f32_e32 v151, v151, v108
	v_sub_f32_e32 v150, v150, v108
	v_sub_f32_e32 v149, v149, v108
	v_sub_f32_e32 v148, v148, v108
	v_sub_f32_e32 v147, v147, v108
	v_sub_f32_e32 v146, v146, v108
	v_sub_f32_e32 v145, v145, v108
	v_sub_f32_e32 v144, v144, v108
	v_sub_f32_e32 v143, v143, v108
	v_sub_f32_e32 v142, v142, v108
	v_sub_f32_e32 v141, v141, v108
	v_sub_f32_e32 v140, v140, v108
	v_sub_f32_e32 v139, v139, v108
	v_sub_f32_e32 v138, v138, v108
	v_sub_f32_e32 v137, v137, v108
	v_sub_f32_e32 v136, v136, v108
	v_sub_f32_e32 v135, v135, v108
	v_sub_f32_e32 v134, v134, v108
	v_sub_f32_e32 v133, v133, v108
	v_sub_f32_e32 v132, v132, v108
	v_sub_f32_e32 v131, v131, v108
	v_sub_f32_e32 v130, v130, v108
	v_sub_f32_e32 v129, v129, v108
	v_sub_f32_e32 v128, v128, v108
	v_mul_f32_e32 v214, v214, v109
	s_branch .LBB0_301
.LBB0_311:
	v_mov_b32_e32 v3, v2
	s_nop 1
	v_permlane32_swap_b32_e32 v2, v3
	v_max_f32_e32 v2, v2, v3
	v_max_f32_e32 v2, v2, v2
	v_max_f32_e32 v2, 0, v2
	v_exp_f32_e64 v3, -v2
	v_add_f32_e32 v243, v243, v2
	v_xor_b32_e32 v80, 0x80000000, v243
	v_mov_b32_e32 v81, v80
	v_mov_b32_e32 v82, v80
	v_mov_b32_e32 v83, v80
	v_mov_b32_e32 v84, v80
	v_mov_b32_e32 v85, v80
	v_mov_b32_e32 v86, v80
	v_mov_b32_e32 v87, v80
	v_mov_b32_e32 v88, v80
	v_mov_b32_e32 v89, v80
	v_mov_b32_e32 v90, v80
	v_mov_b32_e32 v91, v80
	v_mov_b32_e32 v92, v80
	v_mov_b32_e32 v93, v80
	v_mov_b32_e32 v94, v80
	v_mov_b32_e32 v95, v80
	s_and_saveexec_b64 s[0:1], s[2:3]
	ds_write_b32 v240, v3
	s_or_b64 exec, exec, s[0:1]
	v_sub_f32_e32 v127, v127, v2
	v_sub_f32_e32 v126, v126, v2
	v_sub_f32_e32 v125, v125, v2
	v_sub_f32_e32 v124, v124, v2
	v_sub_f32_e32 v123, v123, v2
	v_sub_f32_e32 v122, v122, v2
	v_sub_f32_e32 v121, v121, v2
	v_sub_f32_e32 v120, v120, v2
	v_sub_f32_e32 v119, v119, v2
	v_sub_f32_e32 v118, v118, v2
	v_sub_f32_e32 v117, v117, v2
	v_sub_f32_e32 v116, v116, v2
	v_sub_f32_e32 v115, v115, v2
	v_sub_f32_e32 v114, v114, v2
	v_sub_f32_e32 v113, v113, v2
	v_sub_f32_e32 v112, v112, v2
	v_sub_f32_e32 v111, v111, v2
	v_sub_f32_e32 v110, v110, v2
	v_sub_f32_e32 v109, v109, v2
	v_sub_f32_e32 v108, v108, v2
	v_sub_f32_e32 v107, v107, v2
	v_sub_f32_e32 v106, v106, v2
	v_sub_f32_e32 v105, v105, v2
	v_sub_f32_e32 v104, v104, v2
	v_sub_f32_e32 v103, v103, v2
	v_sub_f32_e32 v102, v102, v2
	v_sub_f32_e32 v101, v101, v2
	v_sub_f32_e32 v100, v100, v2
	v_sub_f32_e32 v99, v99, v2
	v_sub_f32_e32 v98, v98, v2
	v_sub_f32_e32 v97, v97, v2
	v_sub_f32_e32 v96, v96, v2
	v_mul_f32_e32 v250, v250, v3
	s_branch .LBB0_304
